# MF=4 DMA GEMM loops: fragment ds_reads of the first K-step issued right after the barrier, before the DMA issue (on top of the front-interleaved MF=2 loops)
# baseline (speedup 1.0000x reference)
; #define MFMA32(a, b, c) __builtin_amdgcn_mfma_f32_32x32x16_bf16((a), (b), (c), 0, 0, 0)
; template <int MF, int BK, class Epi>
; DI void gemm_phase_t(char* lds, const GemmDesc g, const Epi epi) {
;     ...
;     for (int kt = 0; kt < nk; ++kt) {
;       __syncthreads();
;       const u16* sA = sbase + (kt & 1) * STG;
;       const u16* sB = sA + BM * LS;
;       if (kt + 1 < nk) {
;         u16* nA = sbase + ((kt + 1) & 1) * STG;
; #pragma unroll
;         for (int j = 0; j < APT; ++j) *(u32x4*)(nA + (lr + RSTEP * j) * LS + lc * 8) = ra[j];
; #pragma unroll
;         for (int j = 0; j < BPT; ++j) *(u32x4*)(nA + BM * LS + (lr + RSTEP * j) * LS + lc * 8) = rb[j];
;         if (kt + 2 < nk) {
; #pragma unroll
;           for (int j = 0; j < APT; ++j) ra[j] = *(const u32x4*)(Ap + (size_t)j * RSTEP * g.lda + (kt + 2) * BK);
; #pragma unroll
;           for (int j = 0; j < BPT; ++j) rb[j] = *(const u32x4*)(Bp + (size_t)j * RSTEP * g.ldb + (kt + 2) * BK);
;         }
;       }
;       bf16x8 af[NKK][MF], bfr[NKK][2];
; #pragma unroll
;       for (int kk = 0; kk < NKK; ++kk) {
; #pragma unroll
;         for (int ni = 0; ni < 2; ++ni) bfr[kk][ni] = *(const bf16x8*)(sB + (wn * 64 + ni * 32 + l31) * LS + kk * 16 + h * 8);
; #pragma unroll
;         for (int mi = 0; mi < MF; ++mi) af[kk][mi] = *(const bf16x8*)(sA + (wm * (MF * 32) + mi * 32 + l31) * LS + kk * 16 + h * 8);
;       }
;       __builtin_amdgcn_sched_barrier(0);
; #pragma unroll
;       for (int kk = 0; kk < NKK; ++kk)
; #pragma unroll
;         for (int mi = 0; mi < MF; ++mi)
; #pragma unroll
;           for (int ni = 0; ni < 2; ++ni) acc[mi][ni] = MFMA32(bfr[kk][ni], af[kk][mi], acc[mi][ni]);
;     }
.LBB0_288:
	v_lshl_add_u64 v[186:187], v[164:165], 0, s[4:5]
	v_add_co_u32_e32 v194, vcc, s11, v186
	v_lshl_add_u64 v[204:205], v[168:169], 0, s[4:5]
	s_nop 0
	v_addc_co_u32_e32 v195, vcc, 0, v187, vcc
	v_add_co_u32_e32 v198, vcc, s12, v186
	s_mov_b32 s10, 0x164c000
	s_nop 0
	v_addc_co_u32_e32 v199, vcc, 0, v187, vcc
	v_add_co_u32_e32 v200, vcc, s13, v186
	s_waitcnt lgkmcnt(0)
	s_nop 0
	v_addc_co_u32_e32 v201, vcc, 0, v187, vcc
	v_add_co_u32_e32 v246, vcc, s14, v186
	s_waitcnt vmcnt(6)
	s_barrier
	v_add_u32_e32 v178, s98, v175
	v_add_u32_e32 v179, s98, v176
	v_add_u32_e32 v180, s98, v174
	v_add_u32_e32 v181, s98, v173
	ds_read_b128 v[132:135], v180
	ds_read_b128 v[222:225], v181
	ds_read_b128 v[136:139], v180 offset:2048
	ds_read_b128 v[226:229], v181 offset:2048
	ds_read_b128 v[140:143], v178
	ds_read_b128 v[144:147], v179
	ds_read_b128 v[148:151], v178 offset:2048
	ds_read_b128 v[152:155], v179 offset:2048
	ds_read_b128 v[230:233], v178 offset:4096
	ds_read_b128 v[234:237], v179 offset:4096
	ds_read_b128 v[238:241], v178 offset:6144
	ds_read_b128 v[242:245], v179 offset:6144
	s_nop 0
	v_addc_co_u32_e32 v247, vcc, 0, v187, vcc
	v_add_co_u32_e32 v248, vcc, s10, v204
	s_mov_b32 s10, 0x166c000
	s_nop 0
	v_addc_co_u32_e32 v249, vcc, 0, v205, vcc
	v_add_co_u32_e32 v216, vcc, s10, v204
	s_add_i32 m0, s100, 0xffffff80
	s_nop 0
	global_load_lds_dwordx4 v[194:195], off offset:128
	s_add_i32 m0, s100, 0xf80
	s_nop 0
	global_load_lds_dwordx4 v[198:199], off offset:128
	s_add_i32 m0, s100, 0x1f80
	s_nop 0
	global_load_lds_dwordx4 v[200:201], off offset:128
	s_add_i32 m0, s100, 0x2f80
	s_nop 0
	global_load_lds_dwordx4 v[246:247], off offset:128
	v_addc_co_u32_e32 v217, vcc, 0, v205, vcc
	s_add_i32 m0, s100, 0x3f80
	s_nop 0
	global_load_lds_dwordx4 v[248:249], off offset:128
	s_add_i32 m0, s100, 0x4f80
	s_nop 0
	global_load_lds_dwordx4 v[216:217], off offset:128
	s_waitcnt lgkmcnt(7)
	v_mfma_f32_32x32x16_bf16 v[116:131], v[132:135], v[140:143], v[116:131]
	s_waitcnt lgkmcnt(0)
	s_waitcnt vmcnt(6)
	s_barrier
	v_mfma_f32_32x32x16_bf16 v[100:115], v[136:139], v[140:143], v[100:115]
	v_mfma_f32_32x32x16_bf16 v[84:99], v[132:135], v[148:151], v[84:99]
	v_mfma_f32_32x32x16_bf16 v[68:83], v[136:139], v[148:151], v[68:83]
	v_mfma_f32_32x32x16_bf16 v[52:67], v[132:135], v[230:233], v[52:67]
	v_mfma_f32_32x32x16_bf16 v[36:51], v[136:139], v[230:233], v[36:51]
	v_mfma_f32_32x32x16_bf16 v[20:35], v[132:135], v[238:241], v[20:35]
	v_mfma_f32_32x32x16_bf16 v[4:19], v[136:139], v[238:241], v[4:19]
	s_add_i32 m0, s98, 0xffffff40
	s_nop 0
	global_load_lds_dwordx4 v[194:195], off offset:192
	s_add_i32 m0, s98, 0xf40
	s_nop 0
	global_load_lds_dwordx4 v[198:199], off offset:192
	v_mfma_f32_32x32x16_bf16 v[116:131], v[222:225], v[144:147], v[116:131]
	v_mfma_f32_32x32x16_bf16 v[100:115], v[226:229], v[144:147], v[100:115]
	v_mfma_f32_32x32x16_bf16 v[84:99], v[222:225], v[152:155], v[84:99]
	v_mfma_f32_32x32x16_bf16 v[68:83], v[226:229], v[152:155], v[68:83]
	s_add_i32 m0, s98, 0x1f40
	s_nop 0
	global_load_lds_dwordx4 v[200:201], off offset:192
	s_add_i32 m0, s98, 0x2f40
	s_nop 0
	global_load_lds_dwordx4 v[246:247], off offset:192
	s_add_i32 m0, s98, 0x3f40
	s_nop 0
	global_load_lds_dwordx4 v[248:249], off offset:192
	s_add_i32 m0, s98, 0x4f40
	s_nop 0
	global_load_lds_dwordx4 v[216:217], off offset:192
	v_add_u32_e32 v132, s99, v175
	v_add_u32_e32 v133, s99, v176
	v_add_u32_e32 v134, s99, v174
	v_add_u32_e32 v135, s99, v173
	ds_read_b128 v[178:181], v134
	ds_read_b128 v[182:185], v135
	ds_read_b128 v[186:189], v134 offset:2048
	ds_read_b128 v[190:193], v135 offset:2048
	v_mfma_f32_32x32x16_bf16 v[52:67], v[222:225], v[234:237], v[52:67]
	v_mfma_f32_32x32x16_bf16 v[36:51], v[226:229], v[234:237], v[36:51]
	v_mfma_f32_32x32x16_bf16 v[20:35], v[222:225], v[242:245], v[20:35]
	ds_read_b128 v[204:207], v132
	ds_read_b128 v[218:221], v133
	ds_read_b128 v[222:225], v132 offset:2048
	ds_read_b128 v[230:233], v133 offset:2048
	ds_read_b128 v[234:237], v132 offset:4096
	ds_read_b128 v[238:241], v133 offset:4096
	ds_read_b128 v[246:249], v132 offset:6144
	ds_read_b128 v[198:201], v133 offset:6144
	v_mfma_f32_32x32x16_bf16 v[4:19], v[226:229], v[242:245], v[4:19]
	s_waitcnt lgkmcnt(7)
	v_mfma_f32_32x32x16_bf16 v[116:131], v[178:181], v[204:207], v[116:131]
	s_add_u32 s4, s4, 0x80
	s_addc_u32 s5, s5, 0
	s_cmpk_eq_i32 s4, 0x780
	v_mfma_f32_32x32x16_bf16 v[100:115], v[186:189], v[204:207], v[100:115]
	s_waitcnt lgkmcnt(5)
	v_mfma_f32_32x32x16_bf16 v[84:99], v[178:181], v[222:225], v[84:99]
	v_mfma_f32_32x32x16_bf16 v[68:83], v[186:189], v[222:225], v[68:83]
	s_waitcnt lgkmcnt(3)
	v_mfma_f32_32x32x16_bf16 v[52:67], v[178:181], v[234:237], v[52:67]
	v_mfma_f32_32x32x16_bf16 v[36:51], v[186:189], v[234:237], v[36:51]
	s_waitcnt lgkmcnt(1)
	v_mfma_f32_32x32x16_bf16 v[20:35], v[178:181], v[246:249], v[20:35]
	v_mfma_f32_32x32x16_bf16 v[4:19], v[186:189], v[246:249], v[4:19]
	v_mfma_f32_32x32x16_bf16 v[116:131], v[182:185], v[218:221], v[116:131]
	v_mfma_f32_32x32x16_bf16 v[100:115], v[190:193], v[218:221], v[100:115]
	v_mfma_f32_32x32x16_bf16 v[84:99], v[182:185], v[230:233], v[84:99]
	v_mfma_f32_32x32x16_bf16 v[68:83], v[190:193], v[230:233], v[68:83]
	v_mfma_f32_32x32x16_bf16 v[52:67], v[182:185], v[238:241], v[52:67]
	v_mfma_f32_32x32x16_bf16 v[36:51], v[190:193], v[238:241], v[36:51]
	s_waitcnt lgkmcnt(0)
	v_mfma_f32_32x32x16_bf16 v[20:35], v[182:185], v[198:201], v[20:35]
	v_mfma_f32_32x32x16_bf16 v[4:19], v[190:193], v[198:201], v[4:19]
	s_mov_b32 s101, s100
	s_mov_b32 s100, s99
	s_mov_b32 s99, s98
	s_mov_b32 s98, s101
	s_cbranch_scc0 .LBB0_288
	s_waitcnt vmcnt(6)
	s_barrier
; #define MFMA32(a, b, c) __builtin_amdgcn_mfma_f32_32x32x16_bf16((a), (b), (c), 0, 0, 0)
; DI unsigned pack2(float a, float b) { f2_t v = {a, b}; return __builtin_bit_cast(unsigned, __builtin_convertvector(v, bf2_t)); }
; DI float siluf(float x) { return x * __builtin_amdgcn_rcpf(1.f + __expf(-x)); }
; template <int MF, int BK, class Epi>
; DI void gemm_phase_t(char* lds, const GemmDesc g, const Epi epi) {
;     ...
;       for (int kk = 0; kk < NKK; ++kk) {
; #pragma unroll
;         for (int ni = 0; ni < 2; ++ni) bfr[kk][ni] = *(const bf16x8*)(sB + (wn * 64 + ni * 32 + l31) * LS + kk * 16 + h * 8);
; #pragma unroll
;         for (int mi = 0; mi < MF; ++mi) af[kk][mi] = *(const bf16x8*)(sA + (wm * (MF * 32) + mi * 32 + l31) * LS + kk * 16 + h * 8);
;       }
;       __builtin_amdgcn_sched_barrier(0);
; #pragma unroll
;       for (int kk = 0; kk < NKK; ++kk)
; #pragma unroll
;         for (int mi = 0; mi < MF; ++mi)
; #pragma unroll
;           for (int ni = 0; ni < 2; ++ni) acc[mi][ni] = MFMA32(bfr[kk][ni], af[kk][mi], acc[mi][ni]);
;     }
;     epi(acc, g.mbase + m0 + wm * (MF * 32), n0 + wn * 64, l31, h);
;   template <int MF> DI void operator()(f32x16 (&acc)[MF][2], int mb, int nb, int l31, int h) const {
;     ...
;     for (int mi = 0; mi < MF; ++mi) {
;       const int row = mb + mi * 32 + l31;
; #pragma unroll
;       for (int gp = 0; gp < 2; ++gp) {
;         const int j0 = (nb >> 1) + 16 * h + 8 * gp;
;         float v[8];
; #pragma unroll
;         for (int i = 0; i < 8; ++i) v[i] = siluf(acc[mi][0][8 * gp + i]) * acc[mi][1][8 * gp + i];
;         *(u32x4*)(act + (size_t)row * FF + j0) = (u32x4){pack2(v[0], v[1]), pack2(v[2], v[3]), pack2(v[4], v[5]), pack2(v[6], v[7])};
	v_add_u32_e32 v222, s98, v175
	v_add_u32_e32 v223, s98, v176
	v_add_u32_e32 v224, s98, v174
	v_add_u32_e32 v225, s98, v173
	ds_read_b128 v[132:135], v224
	ds_read_b128 v[136:139], v225
	ds_read_b128 v[140:143], v224 offset:2048
	ds_read_b128 v[144:147], v225 offset:2048
	ds_read_b128 v[148:151], v222
	ds_read_b128 v[152:155], v223
	ds_read_b128 v[178:181], v222 offset:2048
	ds_read_b128 v[182:185], v223 offset:2048
	ds_read_b128 v[186:189], v222 offset:4096
	ds_read_b128 v[190:193], v223 offset:4096
	ds_read_b128 v[204:207], v222 offset:6144
	ds_read_b128 v[218:221], v223 offset:6144
	s_waitcnt lgkmcnt(7)
	v_mfma_f32_32x32x16_bf16 v[116:131], v[132:135], v[148:151], v[116:131]
	s_waitcnt lgkmcnt(0)
	s_waitcnt vmcnt(0)
	s_barrier
	v_mfma_f32_32x32x16_bf16 v[100:115], v[140:143], v[148:151], v[100:115]
	v_mfma_f32_32x32x16_bf16 v[84:99], v[132:135], v[178:181], v[84:99]
	v_mfma_f32_32x32x16_bf16 v[68:83], v[140:143], v[178:181], v[68:83]
	v_mfma_f32_32x32x16_bf16 v[52:67], v[132:135], v[186:189], v[52:67]
	v_mfma_f32_32x32x16_bf16 v[36:51], v[140:143], v[186:189], v[36:51]
	v_mfma_f32_32x32x16_bf16 v[20:35], v[132:135], v[204:207], v[20:35]
	v_mfma_f32_32x32x16_bf16 v[4:19], v[140:143], v[204:207], v[4:19]
	v_mfma_f32_32x32x16_bf16 v[116:131], v[136:139], v[152:155], v[116:131]
	v_mfma_f32_32x32x16_bf16 v[100:115], v[144:147], v[152:155], v[100:115]
	v_mfma_f32_32x32x16_bf16 v[84:99], v[136:139], v[182:185], v[84:99]
	v_mfma_f32_32x32x16_bf16 v[68:83], v[144:147], v[182:185], v[68:83]
	v_mfma_f32_32x32x16_bf16 v[52:67], v[136:139], v[190:193], v[52:67]
	v_mfma_f32_32x32x16_bf16 v[36:51], v[144:147], v[190:193], v[36:51]
	v_mfma_f32_32x32x16_bf16 v[20:35], v[136:139], v[218:221], v[20:35]
	v_mfma_f32_32x32x16_bf16 v[4:19], v[144:147], v[218:221], v[4:19]
	v_add_u32_e32 v226, s99, v175
	v_add_u32_e32 v227, s99, v176
	v_add_u32_e32 v228, s99, v174
	v_add_u32_e32 v229, s99, v173
	s_mov_b32 s101, s100
	s_mov_b32 s100, s99
	s_mov_b32 s99, s98
	s_mov_b32 s98, s101
	ds_read_b128 v[132:135], v226 offset:6144
	ds_read_b128 v[136:139], v227 offset:6144
	ds_read_b128 v[140:143], v227 offset:4096
	ds_read_b128 v[144:147], v227 offset:2048
	ds_read_b128 v[148:151], v226
	ds_read_b128 v[152:155], v227
	ds_read_b128 v[178:181], v229 offset:2048
	ds_read_b128 v[182:185], v228
	ds_read_b128 v[186:189], v229
	ds_read_b128 v[190:193], v226 offset:4096
	ds_read_b128 v[204:207], v226 offset:2048
	ds_read_b128 v[218:221], v228 offset:2048
	s_waitcnt lgkmcnt(4)
	v_mfma_f32_32x32x16_bf16 v[116:131], v[182:185], v[148:151], v[116:131]
	s_waitcnt lgkmcnt(3)
	v_mfma_f32_32x32x16_bf16 v[116:131], v[186:189], v[152:155], v[116:131]
	s_waitcnt lgkmcnt(2)
	v_mfma_f32_32x32x16_bf16 v[52:67], v[182:185], v[190:193], v[52:67]
	s_waitcnt lgkmcnt(0)
	v_mfma_f32_32x32x16_bf16 v[36:51], v[218:221], v[190:193], v[36:51]
	v_mfma_f32_32x32x16_bf16 v[20:35], v[182:185], v[132:135], v[20:35]
	v_mfma_f32_32x32x16_bf16 v[4:19], v[218:221], v[132:135], v[4:19]
	s_nop 5
	v_mul_f32_e32 v135, 0xbfb8aa3b, v116
	v_exp_f32_e32 v135, v135
	v_or_b32_e32 v132, s9, v170
	v_ashrrev_i32_e32 v132, 1, v132
	v_add_u32_e32 v134, s8, v172
	v_add_f32_e32 v135, 1.0, v135
	s_movk_i32 s8, 0x1600
	v_mfma_f32_32x32x16_bf16 v[100:115], v[218:221], v[148:151], v[100:115]
	v_mfma_f32_32x32x16_bf16 v[52:67], v[186:189], v[140:143], v[52:67]
	v_mfma_f32_32x32x16_bf16 v[36:51], v[178:181], v[140:143], v[36:51]
	v_rcp_f32_e32 v140, v135
	v_mul_f32_e32 v135, 0xbfb8aa3b, v117
	v_exp_f32_e32 v135, v135
	s_nop 0
	v_add_f32_e32 v135, 1.0, v135
	v_mfma_f32_32x32x16_bf16 v[100:115], v[178:181], v[152:155], v[100:115]
	v_rcp_f32_e32 v141, v135
	s_nop 0
	v_pk_mul_f32 v[116:117], v[116:117], v[140:141]
	v_mfma_f32_32x32x16_bf16 v[20:35], v[186:189], v[136:139], v[20:35]
	s_nop 7
	v_mul_f32_e64 v100, v100, v116
	v_mul_f32_e64 v101, v101, v117
	v_mul_f32_e32 v116, 0xbfb8aa3b, v118
	v_mul_f32_e32 v117, 0xbfb8aa3b, v119
	v_exp_f32_e32 v116, v116
	v_exp_f32_e32 v117, v117
	v_add_f32_e32 v116, 1.0, v116
	v_add_f32_e32 v117, 1.0, v117
	v_rcp_f32_e32 v116, v116
	v_rcp_f32_e32 v117, v117
	v_mfma_f32_32x32x16_bf16 v[4:19], v[178:181], v[136:139], v[4:19]
	v_or_b32_e32 v136, v132, v171
	v_mov_b64_e32 v[132:133], s[2:3]
	v_mul_f32_e64 v116, v118, v116
	v_mul_f32_e64 v117, v119, v117
	v_ashrrev_i32_e32 v137, 31, v136
	v_pk_mul_f32 v[116:117], v[102:103], v[116:117]
	v_mul_f32_e32 v102, 0xbfb8aa3b, v120
	v_mul_f32_e32 v103, 0xbfb8aa3b, v121
	v_exp_f32_e32 v102, v102
	v_exp_f32_e32 v103, v103
	v_mad_i64_i32 v[138:139], s[4:5], v134, s8, v[132:133]
	v_add_f32_e32 v102, 1.0, v102
	v_add_f32_e32 v103, 1.0, v103
	v_rcp_f32_e32 v102, v102
	v_rcp_f32_e32 v103, v103
	v_mfma_f32_32x32x16_bf16 v[84:99], v[182:185], v[204:207], v[84:99]
	v_mul_f32_e64 v102, v120, v102
	v_mul_f32_e64 v103, v121, v103
	v_mul_f32_e64 v104, v104, v102
	v_mul_f32_e64 v105, v105, v103
	v_mul_f32_e32 v102, 0xbfb8aa3b, v122
	v_mul_f32_e32 v103, 0xbfb8aa3b, v123
	v_exp_f32_e32 v102, v102
	v_exp_f32_e32 v103, v103
	v_cvt_pk_bf16_f32 v104, v104, v105
	v_mfma_f32_32x32x16_bf16 v[84:99], v[186:189], v[144:147], v[84:99]
	v_add_f32_e32 v102, 1.0, v102
	v_add_f32_e32 v103, 1.0, v103
	v_rcp_f32_e32 v102, v102
	v_rcp_f32_e32 v103, v103
	s_nop 0
	v_pk_mul_f32 v[102:103], v[122:123], v[102:103]
	s_nop 0
	v_pk_mul_f32 v[106:107], v[106:107], v[102:103]
	v_cvt_pk_bf16_f32 v102, v100, v101
	v_lshlrev_b64 v[100:101], 1, v[136:137]
	v_cvt_pk_bf16_f32 v103, v116, v117
	v_cvt_pk_bf16_f32 v105, v106, v107
	v_lshl_add_u64 v[106:107], v[138:139], 0, v[100:101]
	global_store_dwordx4 v[106:107], v[102:105], off
	v_mfma_f32_32x32x16_bf16 v[68:83], v[218:221], v[204:207], v[68:83]
	s_nop 0
; DI unsigned pack2(float a, float b) { f2_t v = {a, b}; return __builtin_bit_cast(unsigned, __builtin_convertvector(v, bf2_t)); }
; DI float siluf(float x) { return x * __builtin_amdgcn_rcpf(1.f + __expf(-x)); }
;   template <int MF> DI void operator()(f32x16 (&acc)[MF][2], int mb, int nb, int l31, int h) const {
;     ...
;     for (int mi = 0; mi < MF; ++mi) {
;       const int row = mb + mi * 32 + l31;
; #pragma unroll
;       for (int gp = 0; gp < 2; ++gp) {
;         const int j0 = (nb >> 1) + 16 * h + 8 * gp;
;         float v[8];
; #pragma unroll
;         for (int i = 0; i < 8; ++i) v[i] = siluf(acc[mi][0][8 * gp + i]) * acc[mi][1][8 * gp + i];
;         *(u32x4*)(act + (size_t)row * FF + j0) = (u32x4){pack2(v[0], v[1]), pack2(v[2], v[3]), pack2(v[4], v[5]), pack2(v[6], v[7])};
;       }
	v_mul_f32_e32 v102, 0xbfb8aa3b, v124
	v_mul_f32_e32 v103, 0xbfb8aa3b, v125
	v_mul_f32_e32 v104, 0xbfb8aa3b, v126
	v_mul_f32_e32 v105, 0xbfb8aa3b, v127
	v_exp_f32_e32 v102, v102
	v_exp_f32_e32 v103, v103
	v_exp_f32_e32 v104, v104
	v_exp_f32_e32 v105, v105
	v_add_f32_e32 v102, 1.0, v102
	v_add_f32_e32 v103, 1.0, v103
	v_add_f32_e32 v104, 1.0, v104
	v_add_f32_e32 v105, 1.0, v105
	v_rcp_f32_e32 v102, v102
	v_rcp_f32_e32 v103, v103
	v_rcp_f32_e32 v104, v104
	v_rcp_f32_e32 v105, v105
	v_mfma_f32_32x32x16_bf16 v[68:83], v[178:181], v[144:147], v[68:83]
	v_mul_f32_e64 v102, v124, v102
	v_mul_f32_e64 v103, v125, v103
	v_mul_f32_e64 v104, v126, v104
	v_mul_f32_e64 v105, v127, v105
	v_mul_f32_e64 v102, v108, v102
	v_mul_f32_e64 v103, v109, v103
	v_pk_mul_f32 v[104:105], v[110:111], v[104:105]
	v_mul_f32_e32 v108, 0xbfb8aa3b, v128
	v_mul_f32_e32 v109, 0xbfb8aa3b, v129
	v_mul_f32_e32 v110, 0xbfb8aa3b, v130
	v_mul_f32_e32 v111, 0xbfb8aa3b, v131
	v_exp_f32_e32 v108, v108
	v_exp_f32_e32 v109, v109
	v_exp_f32_e32 v110, v110
	v_exp_f32_e32 v111, v111
	v_add_f32_e32 v108, 1.0, v108
	v_add_f32_e32 v109, 1.0, v109
	v_add_f32_e32 v110, 1.0, v110
	v_add_f32_e32 v111, 1.0, v111
	v_rcp_f32_e32 v108, v108
	v_rcp_f32_e32 v109, v109
	v_rcp_f32_e32 v110, v110
	v_rcp_f32_e32 v111, v111
	v_cvt_pk_bf16_f32 v102, v102, v103
	v_pk_mul_f32 v[108:109], v[128:129], v[108:109]
	v_cvt_pk_bf16_f32 v103, v104, v105
	v_pk_mul_f32 v[110:111], v[130:131], v[110:111]
	v_pk_mul_f32 v[108:109], v[112:113], v[108:109]
	v_pk_mul_f32 v[110:111], v[114:115], v[110:111]
	v_cvt_pk_bf16_f32 v104, v108, v109
	v_cvt_pk_bf16_f32 v105, v110, v111
	global_store_dwordx4 v[106:107], v[102:105], off offset:16
	s_nop 1
	v_mul_f32_e32 v104, 0xbfb8aa3b, v84
	v_mul_f32_e32 v105, 0xbfb8aa3b, v85
	v_exp_f32_e32 v104, v104
	v_exp_f32_e32 v105, v105
	v_or_b32_e32 v102, 32, v134
	v_mad_i64_i32 v[102:103], s[4:5], v102, s8, v[132:133]
	v_add_f32_e32 v104, 1.0, v104
	v_add_f32_e32 v105, 1.0, v105
	v_rcp_f32_e32 v104, v104
	v_rcp_f32_e32 v105, v105
	s_nop 0
	v_pk_mul_f32 v[84:85], v[84:85], v[104:105]
	s_nop 0
	v_pk_mul_f32 v[68:69], v[68:69], v[84:85]
	v_mul_f32_e32 v84, 0xbfb8aa3b, v86
	v_mul_f32_e32 v85, 0xbfb8aa3b, v87
	v_exp_f32_e32 v84, v84
	v_exp_f32_e32 v85, v85
	v_cvt_pk_bf16_f32 v68, v68, v69
	v_add_f32_e32 v84, 1.0, v84
	v_add_f32_e32 v85, 1.0, v85
	v_rcp_f32_e32 v84, v84
	v_rcp_f32_e32 v85, v85
	s_nop 0
	v_pk_mul_f32 v[84:85], v[86:87], v[84:85]
	s_nop 0
	v_pk_mul_f32 v[70:71], v[70:71], v[84:85]
	v_mul_f32_e32 v84, 0xbfb8aa3b, v88
	v_mul_f32_e32 v85, 0xbfb8aa3b, v89
	v_exp_f32_e32 v84, v84
	v_exp_f32_e32 v85, v85
	v_cvt_pk_bf16_f32 v69, v70, v71
	v_add_f32_e32 v84, 1.0, v84
	v_add_f32_e32 v85, 1.0, v85
	v_rcp_f32_e32 v84, v84
	v_rcp_f32_e32 v85, v85
	s_nop 0
	v_pk_mul_f32 v[84:85], v[88:89], v[84:85]
	s_nop 0
	v_pk_mul_f32 v[72:73], v[72:73], v[84:85]
	v_mul_f32_e32 v84, 0xbfb8aa3b, v90
	v_mul_f32_e32 v85, 0xbfb8aa3b, v91
	v_exp_f32_e32 v84, v84
	v_exp_f32_e32 v85, v85
	v_cvt_pk_bf16_f32 v70, v72, v73
	v_lshl_add_u64 v[72:73], v[102:103], 0, v[100:101]
	v_add_f32_e32 v84, 1.0, v84
	v_add_f32_e32 v85, 1.0, v85
	v_rcp_f32_e32 v84, v84
	v_rcp_f32_e32 v85, v85
	s_nop 0
	v_pk_mul_f32 v[84:85], v[90:91], v[84:85]
	s_nop 0
	v_pk_mul_f32 v[74:75], v[74:75], v[84:85]
	s_nop 0
	v_cvt_pk_bf16_f32 v71, v74, v75
	global_store_dwordx4 v[72:73], v[68:71], off
	v_mul_f32_e32 v74, 0xbfb8aa3b, v96
	v_mul_f32_e32 v75, 0xbfb8aa3b, v97
	v_mul_f32_e32 v68, 0xbfb8aa3b, v92
	v_mul_f32_e32 v69, 0xbfb8aa3b, v93
	v_exp_f32_e32 v68, v68
	v_exp_f32_e32 v69, v69
	v_mul_f32_e32 v70, 0xbfb8aa3b, v94
	v_mul_f32_e32 v71, 0xbfb8aa3b, v95
	v_add_f32_e32 v68, 1.0, v68
	v_add_f32_e32 v69, 1.0, v69
	v_rcp_f32_e32 v68, v68
	v_rcp_f32_e32 v69, v69
	v_exp_f32_e32 v70, v70
	v_exp_f32_e32 v71, v71
	v_exp_f32_e32 v74, v74
	v_pk_mul_f32 v[68:69], v[92:93], v[68:69]
	v_exp_f32_e32 v75, v75
	v_pk_mul_f32 v[68:69], v[76:77], v[68:69]
	v_mul_f32_e32 v76, 0xbfb8aa3b, v98
	v_mul_f32_e32 v77, 0xbfb8aa3b, v99
	v_exp_f32_e32 v76, v76
	v_exp_f32_e32 v77, v77
	v_add_f32_e32 v70, 1.0, v70
	v_add_f32_e32 v71, 1.0, v71
	v_add_f32_e32 v74, 1.0, v74
	v_add_f32_e32 v75, 1.0, v75
	v_add_f32_e32 v76, 1.0, v76
	v_add_f32_e32 v77, 1.0, v77
	v_rcp_f32_e32 v70, v70
	v_rcp_f32_e32 v71, v71
	v_rcp_f32_e32 v74, v74
	v_rcp_f32_e32 v75, v75
	v_rcp_f32_e32 v76, v76
	v_rcp_f32_e32 v77, v77
	v_pk_mul_f32 v[70:71], v[94:95], v[70:71]
	v_pk_mul_f32 v[74:75], v[96:97], v[74:75]
	v_pk_mul_f32 v[70:71], v[78:79], v[70:71]
	v_pk_mul_f32 v[76:77], v[98:99], v[76:77]
	v_pk_mul_f32 v[74:75], v[80:81], v[74:75]
	v_pk_mul_f32 v[76:77], v[82:83], v[76:77]
	v_cvt_pk_bf16_f32 v68, v68, v69
	v_cvt_pk_bf16_f32 v69, v70, v71
	v_cvt_pk_bf16_f32 v70, v74, v75
	v_cvt_pk_bf16_f32 v71, v76, v77
	global_store_dwordx4 v[72:73], v[68:71], off offset:16
	s_nop 1
	v_mul_f32_e32 v70, 0xbfb8aa3b, v52
	v_mul_f32_e32 v71, 0xbfb8aa3b, v53
	v_exp_f32_e32 v70, v70
	v_exp_f32_e32 v71, v71
	v_or_b32_e32 v68, 64, v134
	v_mad_i64_i32 v[68:69], s[4:5], v68, s8, v[132:133]
	v_add_f32_e32 v70, 1.0, v70
	v_add_f32_e32 v71, 1.0, v71
	v_rcp_f32_e32 v70, v70
	v_rcp_f32_e32 v71, v71
	s_nop 0
	v_pk_mul_f32 v[52:53], v[52:53], v[70:71]
	s_nop 0
	v_pk_mul_f32 v[36:37], v[36:37], v[52:53]
	v_mul_f32_e32 v52, 0xbfb8aa3b, v54
	v_mul_f32_e32 v53, 0xbfb8aa3b, v55
	v_exp_f32_e32 v52, v52
	v_exp_f32_e32 v53, v53
	v_cvt_pk_bf16_f32 v36, v36, v37
	v_add_f32_e32 v52, 1.0, v52
	v_add_f32_e32 v53, 1.0, v53
	v_rcp_f32_e32 v52, v52
	v_rcp_f32_e32 v53, v53
	s_nop 0
; DI int bid_l() { int t = blockIdx.x; asm volatile("" : "+s"(t)); return t; }
; DI unsigned pack2(float a, float b) { f2_t v = {a, b}; return __builtin_bit_cast(unsigned, __builtin_convertvector(v, bf2_t)); }
; DI float siluf(float x) { return x * __builtin_amdgcn_rcpf(1.f + __expf(-x)); }
; template <int MF, int BK, class Epi>
; DI void gemm_phase_t(char* lds, const GemmDesc g, const Epi epi) {
;     ...
;   for (int t = bid_l(); t < ntiles; t += gridDim.x) {
;   template <int MF> DI void operator()(f32x16 (&acc)[MF][2], int mb, int nb, int l31, int h) const {
;     ...
;     for (int mi = 0; mi < MF; ++mi) {
;       const int row = mb + mi * 32 + l31;
; #pragma unroll
;       for (int gp = 0; gp < 2; ++gp) {
;         const int j0 = (nb >> 1) + 16 * h + 8 * gp;
;         float v[8];
; #pragma unroll
;         for (int i = 0; i < 8; ++i) v[i] = siluf(acc[mi][0][8 * gp + i]) * acc[mi][1][8 * gp + i];
;         *(u32x4*)(act + (size_t)row * FF + j0) = (u32x4){pack2(v[0], v[1]), pack2(v[2], v[3]), pack2(v[4], v[5]), pack2(v[6], v[7])};
;       }
	v_pk_mul_f32 v[52:53], v[54:55], v[52:53]
	s_nop 0
	v_pk_mul_f32 v[38:39], v[38:39], v[52:53]
	v_mul_f32_e32 v52, 0xbfb8aa3b, v56
	v_mul_f32_e32 v53, 0xbfb8aa3b, v57
	v_exp_f32_e32 v52, v52
	v_exp_f32_e32 v53, v53
	v_cvt_pk_bf16_f32 v37, v38, v39
	v_add_f32_e32 v52, 1.0, v52
	v_add_f32_e32 v53, 1.0, v53
	v_rcp_f32_e32 v52, v52
	v_rcp_f32_e32 v53, v53
	s_nop 0
	v_pk_mul_f32 v[52:53], v[56:57], v[52:53]
	s_nop 0
	v_pk_mul_f32 v[40:41], v[40:41], v[52:53]
	v_mul_f32_e32 v52, 0xbfb8aa3b, v58
	v_mul_f32_e32 v53, 0xbfb8aa3b, v59
	v_exp_f32_e32 v52, v52
	v_exp_f32_e32 v53, v53
	v_cvt_pk_bf16_f32 v38, v40, v41
	v_lshl_add_u64 v[40:41], v[68:69], 0, v[100:101]
	v_add_f32_e32 v52, 1.0, v52
	v_add_f32_e32 v53, 1.0, v53
	v_rcp_f32_e32 v52, v52
	v_rcp_f32_e32 v53, v53
	s_nop 0
	v_pk_mul_f32 v[52:53], v[58:59], v[52:53]
	s_nop 0
	v_pk_mul_f32 v[42:43], v[42:43], v[52:53]
	s_nop 0
	v_cvt_pk_bf16_f32 v39, v42, v43
	global_store_dwordx4 v[40:41], v[36:39], off
	v_mul_f32_e32 v42, 0xbfb8aa3b, v64
	v_mul_f32_e32 v43, 0xbfb8aa3b, v65
	v_mul_f32_e32 v36, 0xbfb8aa3b, v60
	v_mul_f32_e32 v37, 0xbfb8aa3b, v61
	v_exp_f32_e32 v36, v36
	v_exp_f32_e32 v37, v37
	v_mul_f32_e32 v38, 0xbfb8aa3b, v62
	v_mul_f32_e32 v39, 0xbfb8aa3b, v63
	v_add_f32_e32 v36, 1.0, v36
	v_add_f32_e32 v37, 1.0, v37
	v_rcp_f32_e32 v36, v36
	v_rcp_f32_e32 v37, v37
	v_exp_f32_e32 v38, v38
	v_exp_f32_e32 v39, v39
	v_exp_f32_e32 v42, v42
	v_pk_mul_f32 v[36:37], v[60:61], v[36:37]
	v_exp_f32_e32 v43, v43
	v_pk_mul_f32 v[36:37], v[44:45], v[36:37]
	v_mul_f32_e32 v44, 0xbfb8aa3b, v66
	v_mul_f32_e32 v45, 0xbfb8aa3b, v67
	v_exp_f32_e32 v44, v44
	v_exp_f32_e32 v45, v45
	v_add_f32_e32 v38, 1.0, v38
	v_add_f32_e32 v39, 1.0, v39
	v_add_f32_e32 v42, 1.0, v42
	v_add_f32_e32 v43, 1.0, v43
	v_add_f32_e32 v44, 1.0, v44
	v_add_f32_e32 v45, 1.0, v45
	v_rcp_f32_e32 v38, v38
	v_rcp_f32_e32 v39, v39
	v_rcp_f32_e32 v42, v42
	v_rcp_f32_e32 v43, v43
	v_rcp_f32_e32 v44, v44
	v_rcp_f32_e32 v45, v45
	v_pk_mul_f32 v[38:39], v[62:63], v[38:39]
	v_pk_mul_f32 v[42:43], v[64:65], v[42:43]
	v_pk_mul_f32 v[38:39], v[46:47], v[38:39]
	v_pk_mul_f32 v[44:45], v[66:67], v[44:45]
	v_pk_mul_f32 v[42:43], v[48:49], v[42:43]
	v_pk_mul_f32 v[44:45], v[50:51], v[44:45]
	v_cvt_pk_bf16_f32 v36, v36, v37
	v_cvt_pk_bf16_f32 v37, v38, v39
	v_cvt_pk_bf16_f32 v38, v42, v43
	v_cvt_pk_bf16_f32 v39, v44, v45
	global_store_dwordx4 v[40:41], v[36:39], off offset:16
	s_nop 1
	v_mul_f32_e32 v38, 0xbfb8aa3b, v20
	v_mul_f32_e32 v39, 0xbfb8aa3b, v21
	v_exp_f32_e32 v38, v38
	v_exp_f32_e32 v39, v39
	v_or_b32_e32 v36, 0x60, v134
	v_mad_i64_i32 v[36:37], s[4:5], v36, s8, v[132:133]
	v_add_f32_e32 v38, 1.0, v38
	v_add_f32_e32 v39, 1.0, v39
	v_rcp_f32_e32 v38, v38
	v_rcp_f32_e32 v39, v39
	v_readlane_b32 s4, v252, 40
	s_add_i32 s7, s7, s4
	s_cmp_ge_i32 s7, s6
	v_pk_mul_f32 v[20:21], v[20:21], v[38:39]
	v_readlane_b32 s5, v252, 41
	v_pk_mul_f32 v[4:5], v[4:5], v[20:21]
	v_mul_f32_e32 v20, 0xbfb8aa3b, v22
	v_mul_f32_e32 v21, 0xbfb8aa3b, v23
	v_exp_f32_e32 v20, v20
	v_exp_f32_e32 v21, v21
	v_cvt_pk_bf16_f32 v4, v4, v5
	v_add_f32_e32 v20, 1.0, v20
	v_add_f32_e32 v21, 1.0, v21
	v_rcp_f32_e32 v20, v20
	v_rcp_f32_e32 v21, v21
	s_nop 0
	v_pk_mul_f32 v[20:21], v[22:23], v[20:21]
	s_nop 0
	v_pk_mul_f32 v[6:7], v[6:7], v[20:21]
	v_mul_f32_e32 v20, 0xbfb8aa3b, v24
	v_mul_f32_e32 v21, 0xbfb8aa3b, v25
	v_exp_f32_e32 v20, v20
	v_exp_f32_e32 v21, v21
	v_cvt_pk_bf16_f32 v5, v6, v7
	v_add_f32_e32 v20, 1.0, v20
	v_add_f32_e32 v21, 1.0, v21
	v_rcp_f32_e32 v20, v20
	v_rcp_f32_e32 v21, v21
	s_nop 0
	v_pk_mul_f32 v[20:21], v[24:25], v[20:21]
	s_nop 0
	v_pk_mul_f32 v[8:9], v[8:9], v[20:21]
	v_mul_f32_e32 v20, 0xbfb8aa3b, v26
	v_mul_f32_e32 v21, 0xbfb8aa3b, v27
	v_exp_f32_e32 v20, v20
	v_exp_f32_e32 v21, v21
	v_cvt_pk_bf16_f32 v6, v8, v9
	v_lshl_add_u64 v[8:9], v[36:37], 0, v[100:101]
	v_add_f32_e32 v20, 1.0, v20
	v_add_f32_e32 v21, 1.0, v21
	v_rcp_f32_e32 v20, v20
	v_rcp_f32_e32 v21, v21
	s_nop 0
	v_pk_mul_f32 v[20:21], v[26:27], v[20:21]
	s_nop 0
	v_pk_mul_f32 v[10:11], v[10:11], v[20:21]
	s_nop 0
	v_cvt_pk_bf16_f32 v7, v10, v11
	global_store_dwordx4 v[8:9], v[4:7], off
	v_mul_f32_e32 v10, 0xbfb8aa3b, v32
	v_mul_f32_e32 v11, 0xbfb8aa3b, v33
	v_mul_f32_e32 v4, 0xbfb8aa3b, v28
	v_mul_f32_e32 v5, 0xbfb8aa3b, v29
	v_exp_f32_e32 v4, v4
	v_exp_f32_e32 v5, v5
	v_mul_f32_e32 v6, 0xbfb8aa3b, v30
	v_mul_f32_e32 v7, 0xbfb8aa3b, v31
	v_add_f32_e32 v4, 1.0, v4
	v_add_f32_e32 v5, 1.0, v5
	v_rcp_f32_e32 v4, v4
	v_rcp_f32_e32 v5, v5
	v_exp_f32_e32 v6, v6
	v_exp_f32_e32 v7, v7
	v_exp_f32_e32 v10, v10
	v_pk_mul_f32 v[4:5], v[28:29], v[4:5]
	v_exp_f32_e32 v11, v11
	v_pk_mul_f32 v[4:5], v[12:13], v[4:5]
	v_mul_f32_e32 v12, 0xbfb8aa3b, v34
	v_mul_f32_e32 v13, 0xbfb8aa3b, v35
	v_exp_f32_e32 v12, v12
	v_exp_f32_e32 v13, v13
	v_add_f32_e32 v6, 1.0, v6
	v_add_f32_e32 v7, 1.0, v7
	v_add_f32_e32 v10, 1.0, v10
	v_add_f32_e32 v11, 1.0, v11
	v_add_f32_e32 v12, 1.0, v12
	v_add_f32_e32 v13, 1.0, v13
	v_rcp_f32_e32 v6, v6
	v_rcp_f32_e32 v7, v7
	v_rcp_f32_e32 v10, v10
	v_rcp_f32_e32 v11, v11
	v_rcp_f32_e32 v12, v12
	v_rcp_f32_e32 v13, v13
	v_pk_mul_f32 v[6:7], v[30:31], v[6:7]
	v_pk_mul_f32 v[10:11], v[32:33], v[10:11]
	v_pk_mul_f32 v[6:7], v[14:15], v[6:7]
	v_pk_mul_f32 v[12:13], v[34:35], v[12:13]
	v_pk_mul_f32 v[10:11], v[16:17], v[10:11]
	v_pk_mul_f32 v[12:13], v[18:19], v[12:13]
	v_cvt_pk_bf16_f32 v4, v4, v5
	v_cvt_pk_bf16_f32 v5, v6, v7
	v_cvt_pk_bf16_f32 v6, v10, v11
	v_cvt_pk_bf16_f32 v7, v12, v13
	global_store_dwordx4 v[8:9], v[4:7], off offset:16
	s_cbranch_scc0 .LBB0_287

; #define MFMA32(a, b, c) __builtin_amdgcn_mfma_f32_32x32x16_bf16((a), (b), (c), 0, 0, 0)
; template <int MF, int BK, class Epi>
; DI void gemm_phase_t(char* lds, const GemmDesc g, const Epi epi) {
;     ...
;     for (int kt = 0; kt < nk; ++kt) {
;       __syncthreads();
;       const u16* sA = sbase + (kt & 1) * STG;
;       const u16* sB = sA + BM * LS;
;       if (kt + 1 < nk) {
;         u16* nA = sbase + ((kt + 1) & 1) * STG;
; #pragma unroll
;         for (int j = 0; j < APT; ++j) *(u32x4*)(nA + (lr + RSTEP * j) * LS + lc * 8) = ra[j];
; #pragma unroll
;         for (int j = 0; j < BPT; ++j) *(u32x4*)(nA + BM * LS + (lr + RSTEP * j) * LS + lc * 8) = rb[j];
;         if (kt + 2 < nk) {
; #pragma unroll
;           for (int j = 0; j < APT; ++j) ra[j] = *(const u32x4*)(Ap + (size_t)j * RSTEP * g.lda + (kt + 2) * BK);
; #pragma unroll
;           for (int j = 0; j < BPT; ++j) rb[j] = *(const u32x4*)(Bp + (size_t)j * RSTEP * g.ldb + (kt + 2) * BK);
;         }
;       }
;       bf16x8 af[NKK][MF], bfr[NKK][2];
; #pragma unroll
;       for (int kk = 0; kk < NKK; ++kk) {
; #pragma unroll
;         for (int ni = 0; ni < 2; ++ni) bfr[kk][ni] = *(const bf16x8*)(sB + (wn * 64 + ni * 32 + l31) * LS + kk * 16 + h * 8);
; #pragma unroll
;         for (int mi = 0; mi < MF; ++mi) af[kk][mi] = *(const bf16x8*)(sA + (wm * (MF * 32) + mi * 32 + l31) * LS + kk * 16 + h * 8);
;       }
;       __builtin_amdgcn_sched_barrier(0);
; #pragma unroll
;       for (int kk = 0; kk < NKK; ++kk)
; #pragma unroll
;         for (int mi = 0; mi < MF; ++mi)
; #pragma unroll
;           for (int ni = 0; ni < 2; ++ni) acc[mi][ni] = MFMA32(bfr[kk][ni], af[kk][mi], acc[mi][ni]);
.LBB0_954:
	v_lshl_add_u64 v[182:183], v[162:163], 0, s[0:1]
	v_add_co_u32_e32 v194, vcc, s5, v182
	v_lshl_add_u64 v[190:191], v[164:165], 0, s[0:1]
	s_nop 0
	v_addc_co_u32_e32 v195, vcc, 0, v183, vcc
	v_add_co_u32_e32 v198, vcc, s11, v182
	s_mov_b32 s4, 0xc4c000
	s_nop 0
	v_addc_co_u32_e32 v199, vcc, 0, v183, vcc
	v_add_co_u32_e32 v200, vcc, s12, v182
	s_waitcnt lgkmcnt(0)
	s_nop 0
	v_addc_co_u32_e32 v201, vcc, 0, v183, vcc
	v_add_co_u32_e32 v204, vcc, s13, v182
	s_waitcnt vmcnt(6)
	s_barrier
	v_add_u32_e32 v174, s98, v172
	v_add_u32_e32 v175, s98, v173
	v_add_u32_e32 v176, s98, v171
	v_add_u32_e32 v177, s98, v170
	ds_read_b128 v[132:135], v176
	ds_read_b128 v[222:225], v177
	ds_read_b128 v[136:139], v176 offset:2048
	ds_read_b128 v[226:229], v177 offset:2048
	ds_read_b128 v[140:143], v174
	ds_read_b128 v[144:147], v175
	ds_read_b128 v[148:151], v174 offset:2048
	ds_read_b128 v[152:155], v175 offset:2048
	ds_read_b128 v[230:233], v174 offset:4096
	ds_read_b128 v[234:237], v175 offset:4096
	ds_read_b128 v[238:241], v174 offset:6144
	ds_read_b128 v[242:245], v175 offset:6144
	s_nop 0
	v_addc_co_u32_e32 v205, vcc, 0, v183, vcc
	v_add_co_u32_e32 v206, vcc, s4, v190
	s_mov_b32 s4, 0xc6c000
	s_nop 0
	v_addc_co_u32_e32 v207, vcc, 0, v191, vcc
	v_add_co_u32_e32 v246, vcc, s4, v190
	s_add_i32 m0, s100, 0xffffff80
	s_nop 0
	global_load_lds_dwordx4 v[194:195], off offset:128
	s_add_i32 m0, s100, 0xf80
	s_nop 0
	global_load_lds_dwordx4 v[198:199], off offset:128
	s_add_i32 m0, s100, 0x1f80
	s_nop 0
	global_load_lds_dwordx4 v[200:201], off offset:128
	s_add_i32 m0, s100, 0x2f80
	s_nop 0
	global_load_lds_dwordx4 v[204:205], off offset:128
	v_addc_co_u32_e32 v247, vcc, 0, v191, vcc
	s_add_i32 m0, s100, 0x3f80
	s_nop 0
	global_load_lds_dwordx4 v[206:207], off offset:128
	s_add_i32 m0, s100, 0x4f80
	s_nop 0
	global_load_lds_dwordx4 v[246:247], off offset:128
	s_waitcnt lgkmcnt(7)
	v_mfma_f32_32x32x16_bf16 v[116:131], v[132:135], v[140:143], v[116:131]
	s_waitcnt lgkmcnt(0)
	s_waitcnt vmcnt(6)
	s_barrier
	v_mfma_f32_32x32x16_bf16 v[100:115], v[136:139], v[140:143], v[100:115]
	v_mfma_f32_32x32x16_bf16 v[84:99], v[132:135], v[148:151], v[84:99]
	v_mfma_f32_32x32x16_bf16 v[68:83], v[136:139], v[148:151], v[68:83]
	v_mfma_f32_32x32x16_bf16 v[52:67], v[132:135], v[230:233], v[52:67]
	v_mfma_f32_32x32x16_bf16 v[36:51], v[136:139], v[230:233], v[36:51]
	v_mfma_f32_32x32x16_bf16 v[20:35], v[132:135], v[238:241], v[20:35]
	v_mfma_f32_32x32x16_bf16 v[4:19], v[136:139], v[238:241], v[4:19]
	s_add_i32 m0, s98, 0xffffff40
	s_nop 0
	global_load_lds_dwordx4 v[194:195], off offset:192
	s_add_i32 m0, s98, 0xf40
	s_nop 0
	global_load_lds_dwordx4 v[198:199], off offset:192
	v_mfma_f32_32x32x16_bf16 v[116:131], v[222:225], v[144:147], v[116:131]
	v_mfma_f32_32x32x16_bf16 v[100:115], v[226:229], v[144:147], v[100:115]
	v_mfma_f32_32x32x16_bf16 v[84:99], v[222:225], v[152:155], v[84:99]
	v_mfma_f32_32x32x16_bf16 v[68:83], v[226:229], v[152:155], v[68:83]
	s_add_i32 m0, s98, 0x1f40
	s_nop 0
	global_load_lds_dwordx4 v[200:201], off offset:192
	s_add_i32 m0, s98, 0x2f40
	s_nop 0
	global_load_lds_dwordx4 v[204:205], off offset:192
	s_add_i32 m0, s98, 0x3f40
	s_nop 0
	global_load_lds_dwordx4 v[206:207], off offset:192
	s_add_i32 m0, s98, 0x4f40
	s_nop 0
	global_load_lds_dwordx4 v[246:247], off offset:192
	v_add_u32_e32 v132, s99, v172
	v_add_u32_e32 v133, s99, v173
	v_add_u32_e32 v134, s99, v171
	v_add_u32_e32 v135, s99, v170
	ds_read_b128 v[174:177], v134
	ds_read_b128 v[178:181], v135
	ds_read_b128 v[182:185], v134 offset:2048
	ds_read_b128 v[186:189], v135 offset:2048
	v_mfma_f32_32x32x16_bf16 v[52:67], v[222:225], v[234:237], v[52:67]
	v_mfma_f32_32x32x16_bf16 v[36:51], v[226:229], v[234:237], v[36:51]
	v_mfma_f32_32x32x16_bf16 v[20:35], v[222:225], v[242:245], v[20:35]
	ds_read_b128 v[190:193], v132
	ds_read_b128 v[218:221], v133
	ds_read_b128 v[222:225], v132 offset:2048
	ds_read_b128 v[230:233], v133 offset:2048
	ds_read_b128 v[234:237], v132 offset:4096
	ds_read_b128 v[238:241], v133 offset:4096
	ds_read_b128 v[246:249], v132 offset:6144
	ds_read_b128 v[204:207], v133 offset:6144
	v_mfma_f32_32x32x16_bf16 v[4:19], v[226:229], v[242:245], v[4:19]
	s_waitcnt lgkmcnt(7)
	v_mfma_f32_32x32x16_bf16 v[116:131], v[174:177], v[190:193], v[116:131]
	s_add_u32 s0, s0, 0x80
	s_addc_u32 s1, s1, 0
	s_cmpk_eq_i32 s0, 0x780
	v_mfma_f32_32x32x16_bf16 v[100:115], v[182:185], v[190:193], v[100:115]
	s_waitcnt lgkmcnt(5)
	v_mfma_f32_32x32x16_bf16 v[84:99], v[174:177], v[222:225], v[84:99]
	v_mfma_f32_32x32x16_bf16 v[68:83], v[182:185], v[222:225], v[68:83]
	s_waitcnt lgkmcnt(3)
	v_mfma_f32_32x32x16_bf16 v[52:67], v[174:177], v[234:237], v[52:67]
	v_mfma_f32_32x32x16_bf16 v[36:51], v[182:185], v[234:237], v[36:51]
	s_waitcnt lgkmcnt(1)
	v_mfma_f32_32x32x16_bf16 v[20:35], v[174:177], v[246:249], v[20:35]
	v_mfma_f32_32x32x16_bf16 v[4:19], v[182:185], v[246:249], v[4:19]
	v_mfma_f32_32x32x16_bf16 v[116:131], v[178:181], v[218:221], v[116:131]
	v_mfma_f32_32x32x16_bf16 v[100:115], v[186:189], v[218:221], v[100:115]
	v_mfma_f32_32x32x16_bf16 v[84:99], v[178:181], v[230:233], v[84:99]
	v_mfma_f32_32x32x16_bf16 v[68:83], v[186:189], v[230:233], v[68:83]
	v_mfma_f32_32x32x16_bf16 v[52:67], v[178:181], v[238:241], v[52:67]
	v_mfma_f32_32x32x16_bf16 v[36:51], v[186:189], v[238:241], v[36:51]
	s_waitcnt lgkmcnt(0)
	v_mfma_f32_32x32x16_bf16 v[20:35], v[178:181], v[204:207], v[20:35]
	v_mfma_f32_32x32x16_bf16 v[4:19], v[186:189], v[204:207], v[4:19]
	s_mov_b32 s101, s100
	s_mov_b32 s100, s99
	s_mov_b32 s99, s98
	s_mov_b32 s98, s101
	s_cbranch_scc0 .LBB0_954
	s_waitcnt vmcnt(6)
	s_barrier
; #define MFMA32(a, b, c) __builtin_amdgcn_mfma_f32_32x32x16_bf16((a), (b), (c), 0, 0, 0)
; DI unsigned pack2(float a, float b) { f2_t v = {a, b}; return __builtin_bit_cast(unsigned, __builtin_convertvector(v, bf2_t)); }
; template <int MF, int BK, class Epi>
; DI void gemm_phase_t(char* lds, const GemmDesc g, const Epi epi) {
;     ...
;       for (int kk = 0; kk < NKK; ++kk) {
; #pragma unroll
;         for (int ni = 0; ni < 2; ++ni) bfr[kk][ni] = *(const bf16x8*)(sB + (wn * 64 + ni * 32 + l31) * LS + kk * 16 + h * 8);
; #pragma unroll
;         for (int mi = 0; mi < MF; ++mi) af[kk][mi] = *(const bf16x8*)(sA + (wm * (MF * 32) + mi * 32 + l31) * LS + kk * 16 + h * 8);
;       }
;       __builtin_amdgcn_sched_barrier(0);
; #pragma unroll
;       for (int kk = 0; kk < NKK; ++kk)
; #pragma unroll
;         for (int mi = 0; mi < MF; ++mi)
; #pragma unroll
;           for (int ni = 0; ni < 2; ++ni) acc[mi][ni] = MFMA32(bfr[kk][ni], af[kk][mi], acc[mi][ni]);
;   template <int MF> DI void operator()(f32x16 (&acc)[MF][2], int mb, int nb, int l31, int h) const {
;     ...
;       for (int g4 = 0; g4 < 4; ++g4) {
;         const int col0 = nb + 16 * g4 + 8 * h;
;         u16* dst = (col0 < 2560) ? zhg + (size_t)row * 2560 + col0 : zhy + (size_t)row * 1536 + (col0 - 2560);
;         *(u32x4*)dst = (u32x4){pack2(acc[mi][0][4 * g4], acc[mi][0][4 * g4 + 1]), pack2(acc[mi][0][4 * g4 + 2], acc[mi][0][4 * g4 + 3]),
;                                pack2(acc[mi][1][4 * g4], acc[mi][1][4 * g4 + 1]), pack2(acc[mi][1][4 * g4 + 2], acc[mi][1][4 * g4 + 3])};
	v_add_u32_e32 v222, s98, v172
	v_add_u32_e32 v223, s98, v173
	v_add_u32_e32 v224, s98, v171
	v_add_u32_e32 v225, s98, v170
	ds_read_b128 v[132:135], v224
	ds_read_b128 v[136:139], v225
	ds_read_b128 v[140:143], v224 offset:2048
	ds_read_b128 v[144:147], v225 offset:2048
	ds_read_b128 v[148:151], v222
	ds_read_b128 v[152:155], v223
	ds_read_b128 v[162:165], v222 offset:2048
	ds_read_b128 v[174:177], v223 offset:2048
	ds_read_b128 v[178:181], v222 offset:4096
	ds_read_b128 v[182:185], v223 offset:4096
	ds_read_b128 v[186:189], v222 offset:6144
	ds_read_b128 v[190:193], v223 offset:6144
	s_waitcnt lgkmcnt(7)
	v_mfma_f32_32x32x16_bf16 v[116:131], v[132:135], v[148:151], v[116:131]
	s_waitcnt lgkmcnt(0)
	s_waitcnt vmcnt(0)
	s_barrier
	v_mfma_f32_32x32x16_bf16 v[100:115], v[140:143], v[148:151], v[100:115]
	v_mfma_f32_32x32x16_bf16 v[84:99], v[132:135], v[162:165], v[84:99]
	v_mfma_f32_32x32x16_bf16 v[68:83], v[140:143], v[162:165], v[68:83]
	v_mfma_f32_32x32x16_bf16 v[52:67], v[132:135], v[178:181], v[52:67]
	v_mfma_f32_32x32x16_bf16 v[36:51], v[140:143], v[178:181], v[36:51]
	v_mfma_f32_32x32x16_bf16 v[20:35], v[132:135], v[186:189], v[20:35]
	v_mfma_f32_32x32x16_bf16 v[4:19], v[140:143], v[186:189], v[4:19]
	v_mfma_f32_32x32x16_bf16 v[116:131], v[136:139], v[152:155], v[116:131]
	v_mfma_f32_32x32x16_bf16 v[100:115], v[144:147], v[152:155], v[100:115]
	v_mfma_f32_32x32x16_bf16 v[84:99], v[136:139], v[174:177], v[84:99]
	v_mfma_f32_32x32x16_bf16 v[68:83], v[144:147], v[174:177], v[68:83]
	v_mfma_f32_32x32x16_bf16 v[52:67], v[136:139], v[182:185], v[52:67]
	v_mfma_f32_32x32x16_bf16 v[36:51], v[144:147], v[182:185], v[36:51]
	v_mfma_f32_32x32x16_bf16 v[20:35], v[136:139], v[190:193], v[20:35]
	v_mfma_f32_32x32x16_bf16 v[4:19], v[144:147], v[190:193], v[4:19]
	v_add_u32_e32 v226, s99, v172
	v_add_u32_e32 v227, s99, v173
	v_add_u32_e32 v228, s99, v171
	v_add_u32_e32 v229, s99, v170
	s_mov_b32 s101, s100
	s_mov_b32 s100, s99
	s_mov_b32 s99, s98
	s_mov_b32 s98, s101
	ds_read_b128 v[132:135], v226 offset:6144
	ds_read_b128 v[136:139], v227 offset:6144
	ds_read_b128 v[140:143], v227 offset:4096
	ds_read_b128 v[144:147], v227 offset:2048
	ds_read_b128 v[148:151], v226
	ds_read_b128 v[152:155], v227
	ds_read_b128 v[162:165], v229 offset:2048
	ds_read_b128 v[174:177], v228
	ds_read_b128 v[178:181], v229
	ds_read_b128 v[182:185], v226 offset:4096
	ds_read_b128 v[186:189], v226 offset:2048
	ds_read_b128 v[190:193], v228 offset:2048
	s_waitcnt lgkmcnt(4)
	v_mfma_f32_32x32x16_bf16 v[116:131], v[174:177], v[148:151], v[116:131]
	s_movk_i32 s0, 0xa00
	s_movk_i32 s11, 0x1400
	s_movk_i32 s14, 0xc00
	s_movk_i32 s16, 0xec00
	s_mov_b32 s17, -1
	s_movk_i32 s18, 0xec20
	s_mov_b32 s19, -1
	s_waitcnt lgkmcnt(0)
	v_mfma_f32_32x32x16_bf16 v[100:115], v[190:193], v[148:151], v[100:115]
	v_add_u32_e32 v148, s2, v168
	s_movk_i32 s20, 0xec40
	s_movk_i32 s2, 0x9e0
	s_mov_b32 s21, -1
	s_movk_i32 s24, 0xec60
	s_movk_i32 s4, 0x9d0
	s_mov_b64 s[22:23], 0x60
	v_mfma_f32_32x32x16_bf16 v[52:67], v[174:177], v[182:185], v[52:67]
	s_mov_b32 s25, -1
	v_mfma_f32_32x32x16_bf16 v[36:51], v[190:193], v[182:185], v[36:51]
	v_mfma_f32_32x32x16_bf16 v[20:35], v[174:177], v[132:135], v[20:35]
	v_mfma_f32_32x32x16_bf16 v[4:19], v[190:193], v[132:135], v[4:19]
	v_mov_b64_e32 v[134:135], s[6:7]
	v_mov_b64_e32 v[132:133], s[8:9]
	v_mfma_f32_32x32x16_bf16 v[84:99], v[174:177], v[186:189], v[84:99]
	v_mfma_f32_32x32x16_bf16 v[68:83], v[190:193], v[186:189], v[68:83]
	v_mfma_f32_32x32x16_bf16 v[116:131], v[178:181], v[152:155], v[116:131]
	v_mfma_f32_32x32x16_bf16 v[100:115], v[162:165], v[152:155], v[100:115]
	s_nop 10
	v_cvt_pk_bf16_f32 v116, v116, v117
	v_cvt_pk_bf16_f32 v117, v118, v119
	v_mfma_f32_32x32x16_bf16 v[52:67], v[178:181], v[140:143], v[52:67]
	v_cvt_pk_bf16_f32 v118, v100, v101
	v_cvt_pk_bf16_f32 v119, v102, v103
	v_mfma_f32_32x32x16_bf16 v[36:51], v[162:165], v[140:143], v[36:51]
	v_or_b32_e32 v140, s3, v169
	v_ashrrev_i32_e32 v141, 31, v140
	v_cmp_gt_i32_e32 vcc, s0, v140
	v_mad_i64_i32 v[142:143], s[0:1], v148, s14, v[132:133]
	v_cmp_gt_i32_e64 s[2:3], s2, v140
	v_cmp_gt_i32_e64 s[4:5], s4, v140
	v_mfma_f32_32x32x16_bf16 v[20:35], v[178:181], v[136:139], v[20:35]
	s_nop 1
	v_cvt_pk_bf16_f32 v52, v52, v53
	v_cvt_pk_bf16_f32 v53, v54, v55
	s_nop 0
	v_cvt_pk_bf16_f32 v54, v36, v37
	v_cvt_pk_bf16_f32 v55, v38, v39
	v_mfma_f32_32x32x16_bf16 v[4:19], v[162:165], v[136:139], v[4:19]
	v_mad_i64_i32 v[138:139], s[0:1], v148, s11, v[134:135]
	v_lshlrev_b64 v[136:137], 1, v[140:141]
	v_mov_b32_e32 v141, v3
	s_movk_i32 s0, 0x9f0
	v_cmp_gt_i32_e64 s[0:1], s0, v140
	v_cvt_pk_bf16_f32 v20, v20, v21
	v_mfma_f32_32x32x16_bf16 v[84:99], v[178:181], v[144:147], v[84:99]
	v_cvt_pk_bf16_f32 v21, v22, v23
	s_nop 3
	v_cvt_pk_bf16_f32 v22, v4, v5
	v_cvt_pk_bf16_f32 v23, v6, v7
	v_mfma_f32_32x32x16_bf16 v[68:83], v[162:165], v[144:147], v[68:83]
	v_lshl_add_u64 v[144:145], v[138:139], 0, v[136:137]
	v_lshlrev_b64 v[138:139], 1, v[140:141]
	v_lshl_add_u64 v[142:143], v[142:143], 0, v[138:139]
	v_lshl_add_u64 v[146:147], v[142:143], 0, s[16:17]
	v_cndmask_b32_e32 v147, v147, v145, vcc
	v_cndmask_b32_e32 v146, v146, v144, vcc
	v_lshl_add_u64 v[100:101], v[144:145], 0, 32
	v_lshl_add_u64 v[102:103], v[142:143], 0, s[18:19]
	global_store_dwordx4 v[146:147], v[116:119], off
	v_cvt_pk_bf16_f32 v84, v84, v85
	v_cvt_pk_bf16_f32 v85, v86, v87
	v_cndmask_b32_e64 v117, v103, v101, s[0:1]
	v_cndmask_b32_e64 v116, v102, v100, s[0:1]
	v_cvt_pk_bf16_f32 v100, v120, v121
	v_cvt_pk_bf16_f32 v101, v122, v123
	v_cvt_pk_bf16_f32 v102, v104, v105
; DI int bid_l() { int t = blockIdx.x; asm volatile("" : "+s"(t)); return t; }
; DI unsigned pack2(float a, float b) { f2_t v = {a, b}; return __builtin_bit_cast(unsigned, __builtin_convertvector(v, bf2_t)); }
; template <int MF, int BK, class Epi>
; DI void gemm_phase_t(char* lds, const GemmDesc g, const Epi epi) {
;     ...
;   for (int t = bid_l(); t < ntiles; t += gridDim.x) {
;   template <int MF> DI void operator()(f32x16 (&acc)[MF][2], int mb, int nb, int l31, int h) const {
;     ...
;     for (int mi = 0; mi < MF; ++mi) {
;       const int row = mb + mi * 32 + l31;
; #pragma unroll
;       for (int g4 = 0; g4 < 4; ++g4) {
;         const int col0 = nb + 16 * g4 + 8 * h;
;         u16* dst = (col0 < 2560) ? zhg + (size_t)row * 2560 + col0 : zhy + (size_t)row * 1536 + (col0 - 2560);
;         *(u32x4*)dst = (u32x4){pack2(acc[mi][0][4 * g4], acc[mi][0][4 * g4 + 1]), pack2(acc[mi][0][4 * g4 + 2], acc[mi][0][4 * g4 + 3]),
;                                pack2(acc[mi][1][4 * g4], acc[mi][1][4 * g4 + 1]), pack2(acc[mi][1][4 * g4 + 2], acc[mi][1][4 * g4 + 3])};
	v_cvt_pk_bf16_f32 v103, v106, v107
	global_store_dwordx4 v[116:117], v[100:103], off
	v_cvt_pk_bf16_f32 v86, v68, v69
	v_cvt_pk_bf16_f32 v87, v70, v71
	v_lshl_add_u64 v[100:101], v[144:145], 0, 64
	v_lshl_add_u64 v[102:103], v[142:143], 0, s[20:21]
	v_cndmask_b32_e64 v105, v103, v101, s[2:3]
	v_cndmask_b32_e64 v104, v102, v100, s[2:3]
	v_cvt_pk_bf16_f32 v100, v124, v125
	v_cvt_pk_bf16_f32 v101, v126, v127
	v_cvt_pk_bf16_f32 v102, v108, v109
	v_cvt_pk_bf16_f32 v103, v110, v111
	global_store_dwordx4 v[104:105], v[100:103], off
	s_nop 1
	v_lshl_add_u64 v[100:101], v[144:145], 0, s[22:23]
	v_lshl_add_u64 v[102:103], v[142:143], 0, s[24:25]
	v_cndmask_b32_e64 v105, v103, v101, s[4:5]
	v_cndmask_b32_e64 v104, v102, v100, s[4:5]
	v_cvt_pk_bf16_f32 v100, v128, v129
	v_cvt_pk_bf16_f32 v101, v130, v131
	v_cvt_pk_bf16_f32 v102, v112, v113
	v_cvt_pk_bf16_f32 v103, v114, v115
	global_store_dwordx4 v[104:105], v[100:103], off
	s_nop 1
	v_or_b32_e32 v102, 32, v148
	v_mad_i64_i32 v[100:101], s[12:13], v102, s14, v[132:133]
	v_mad_i64_i32 v[102:103], s[12:13], v102, s11, v[134:135]
	v_lshl_add_u64 v[100:101], v[100:101], 0, v[138:139]
	v_lshl_add_u64 v[102:103], v[102:103], 0, v[136:137]
	v_lshl_add_u64 v[104:105], v[100:101], 0, s[16:17]
	v_cndmask_b32_e32 v105, v105, v103, vcc
	v_cndmask_b32_e32 v104, v104, v102, vcc
	v_lshl_add_u64 v[68:69], v[102:103], 0, 32
	v_lshl_add_u64 v[70:71], v[100:101], 0, s[18:19]
	global_store_dwordx4 v[104:105], v[84:87], off
	s_nop 1
	v_cndmask_b32_e64 v85, v71, v69, s[0:1]
	v_cndmask_b32_e64 v84, v70, v68, s[0:1]
	v_cvt_pk_bf16_f32 v68, v88, v89
	v_cvt_pk_bf16_f32 v69, v90, v91
	v_cvt_pk_bf16_f32 v70, v72, v73
	v_cvt_pk_bf16_f32 v71, v74, v75
	global_store_dwordx4 v[84:85], v[68:71], off
	s_nop 1
	v_lshl_add_u64 v[68:69], v[102:103], 0, 64
	v_lshl_add_u64 v[70:71], v[100:101], 0, s[20:21]
	v_cndmask_b32_e64 v73, v71, v69, s[2:3]
	v_cndmask_b32_e64 v72, v70, v68, s[2:3]
	v_cvt_pk_bf16_f32 v68, v92, v93
	v_cvt_pk_bf16_f32 v69, v94, v95
	v_cvt_pk_bf16_f32 v70, v76, v77
	v_cvt_pk_bf16_f32 v71, v78, v79
	global_store_dwordx4 v[72:73], v[68:71], off
	s_nop 1
	v_lshl_add_u64 v[68:69], v[102:103], 0, s[22:23]
	v_lshl_add_u64 v[70:71], v[100:101], 0, s[24:25]
	v_cndmask_b32_e64 v73, v71, v69, s[4:5]
	v_cndmask_b32_e64 v72, v70, v68, s[4:5]
	v_cvt_pk_bf16_f32 v68, v96, v97
	v_cvt_pk_bf16_f32 v69, v98, v99
	v_cvt_pk_bf16_f32 v70, v80, v81
	v_cvt_pk_bf16_f32 v71, v82, v83
	global_store_dwordx4 v[72:73], v[68:71], off
	s_nop 1
	v_or_b32_e32 v70, 64, v148
	v_mad_i64_i32 v[68:69], s[12:13], v70, s14, v[132:133]
	v_mad_i64_i32 v[70:71], s[12:13], v70, s11, v[134:135]
	v_lshl_add_u64 v[68:69], v[68:69], 0, v[138:139]
	v_lshl_add_u64 v[70:71], v[70:71], 0, v[136:137]
	v_lshl_add_u64 v[72:73], v[68:69], 0, s[16:17]
	v_cndmask_b32_e32 v73, v73, v71, vcc
	v_cndmask_b32_e32 v72, v72, v70, vcc
	v_lshl_add_u64 v[36:37], v[70:71], 0, 32
	v_lshl_add_u64 v[38:39], v[68:69], 0, s[18:19]
	global_store_dwordx4 v[72:73], v[52:55], off
	s_nop 1
	v_cndmask_b32_e64 v53, v39, v37, s[0:1]
	v_cndmask_b32_e64 v52, v38, v36, s[0:1]
	v_cvt_pk_bf16_f32 v36, v56, v57
	v_cvt_pk_bf16_f32 v37, v58, v59
	v_cvt_pk_bf16_f32 v38, v40, v41
	v_cvt_pk_bf16_f32 v39, v42, v43
	global_store_dwordx4 v[52:53], v[36:39], off
	s_nop 1
	v_lshl_add_u64 v[36:37], v[70:71], 0, 64
	v_lshl_add_u64 v[38:39], v[68:69], 0, s[20:21]
	v_cndmask_b32_e64 v41, v39, v37, s[2:3]
	v_cndmask_b32_e64 v40, v38, v36, s[2:3]
	v_cvt_pk_bf16_f32 v36, v60, v61
	v_cvt_pk_bf16_f32 v37, v62, v63
	v_cvt_pk_bf16_f32 v38, v44, v45
	v_cvt_pk_bf16_f32 v39, v46, v47
	global_store_dwordx4 v[40:41], v[36:39], off
	s_nop 1
	v_lshl_add_u64 v[36:37], v[70:71], 0, s[22:23]
	v_lshl_add_u64 v[38:39], v[68:69], 0, s[24:25]
	v_cndmask_b32_e64 v41, v39, v37, s[4:5]
	v_cndmask_b32_e64 v40, v38, v36, s[4:5]
	v_cvt_pk_bf16_f32 v36, v64, v65
	v_cvt_pk_bf16_f32 v37, v66, v67
	v_cvt_pk_bf16_f32 v38, v48, v49
	v_cvt_pk_bf16_f32 v39, v50, v51
	global_store_dwordx4 v[40:41], v[36:39], off
	s_nop 1
	v_or_b32_e32 v38, 0x60, v148
	v_mad_i64_i32 v[36:37], s[12:13], v38, s14, v[132:133]
	v_mad_i64_i32 v[38:39], s[12:13], v38, s11, v[134:135]
	v_lshl_add_u64 v[36:37], v[36:37], 0, v[138:139]
	v_lshl_add_u64 v[38:39], v[38:39], 0, v[136:137]
	v_lshl_add_u64 v[40:41], v[36:37], 0, s[16:17]
	v_cndmask_b32_e32 v41, v41, v39, vcc
	v_cndmask_b32_e32 v40, v40, v38, vcc
	v_lshl_add_u64 v[4:5], v[38:39], 0, 32
	v_lshl_add_u64 v[6:7], v[36:37], 0, s[18:19]
	global_store_dwordx4 v[40:41], v[20:23], off
	s_nop 1
	v_cndmask_b32_e64 v21, v7, v5, s[0:1]
	v_cndmask_b32_e64 v20, v6, v4, s[0:1]
	v_cvt_pk_bf16_f32 v4, v24, v25
	v_cvt_pk_bf16_f32 v5, v26, v27
	v_cvt_pk_bf16_f32 v6, v8, v9
	v_cvt_pk_bf16_f32 v7, v10, v11
	global_store_dwordx4 v[20:21], v[4:7], off
	v_readlane_b32 s0, v252, 40
	s_add_i32 s10, s10, s0
	v_lshl_add_u64 v[4:5], v[38:39], 0, 64
	v_lshl_add_u64 v[6:7], v[36:37], 0, s[20:21]
	v_cndmask_b32_e64 v9, v7, v5, s[2:3]
	v_cndmask_b32_e64 v8, v6, v4, s[2:3]
	v_cvt_pk_bf16_f32 v4, v28, v29
	v_cvt_pk_bf16_f32 v5, v30, v31
	v_cvt_pk_bf16_f32 v6, v12, v13
	v_cvt_pk_bf16_f32 v7, v14, v15
	global_store_dwordx4 v[8:9], v[4:7], off
	s_cmpk_gt_i32 s10, 0x10ff
	v_readlane_b32 s1, v252, 41
	v_lshl_add_u64 v[4:5], v[38:39], 0, s[22:23]
	v_lshl_add_u64 v[6:7], v[36:37], 0, s[24:25]
	v_cndmask_b32_e64 v9, v7, v5, s[4:5]
	v_cndmask_b32_e64 v8, v6, v4, s[4:5]
	v_cvt_pk_bf16_f32 v4, v32, v33
	v_cvt_pk_bf16_f32 v5, v34, v35
	v_cvt_pk_bf16_f32 v6, v16, v17
	v_cvt_pk_bf16_f32 v7, v18, v19
	global_store_dwordx4 v[8:9], v[4:7], off
	s_cbranch_scc0 .LBB0_953
